# final RMSNorm rows mapped token-local (rows 16*gw'..+15) so the last seam is XCD-local too (14 local seams)
# baseline (speedup 1.0000x reference)
.LBB0_2087:
	s_lshl_b32 s0, s2, 3
	s_add_i32 s17, s96, s0
	s_and_b32 s0, s2, 7
	s_lshr_b32 s18, s2, 3
	s_lshl_b32 s0, s0, 5
	s_add_i32 s0, s0, s18
	s_lshl_b32 s0, s0, 3
	s_add_i32 s0, s0, s96
	s_lshl_b32 s0, s0, 4
	s_add_i32 s18, s0, 16
	s_lshl_b32 s19, s94, 3
	s_cmp_eq_u32 s94, 0x100
	s_cselect_b32 s2, s0, s17
	s_cselect_b32 s16, s18, 0x8000
	s_cselect_b32 s19, 1, s19
	s_cmpk_gt_i32 s2, 0x7fff
	s_cbranch_scc1 .LBB0_2090
	s_mov_b32 s4, s19
	s_ashr_i32 s3, s2, 31
	s_lshl_b64 s[0:1], s[2:3], 11
	s_ashr_i32 s5, s4, 31
	s_waitcnt vmcnt(0)
	v_lshl_or_b32 v4, v251, 3, s0
	v_mov_b32_e32 v5, s1
	s_lshl_b64 s[6:7], s[4:5], 11
	s_lshl_b64 s[8:9], s[2:3], 6
	s_lshl_b64 s[10:11], s[4:5], 6
	s_lshl_b64 s[0:1], s[2:3], 12
	s_add_u32 s0, s88, s0
	v_lshlrev_b32_e32 v0, 4, v251
	s_waitcnt lgkmcnt(0)
	v_mov_b32_e32 v1, 0
	s_addc_u32 s1, s89, s1
	v_lshl_add_u64 v[6:7], s[0:1], 0, v[0:1]
	s_mov_b64 s[0:1], 0xc00
	v_lshl_add_u64 v[2:3], s[78:79], 0, v[0:1]
	v_lshl_add_u64 v[6:7], v[6:7], 0, s[0:1]
	s_lshl_b64 s[12:13], s[4:5], 12
	v_mov_b32_e32 v0, 0x5900000
	v_mov_b32_e32 v8, 0x358637bd
	s_mov_b32 s3, 0xf800000
	v_mov_b32_e32 v9, 0x260
	s_mov_b32 s5, 0x6400000
.LBB0_2089:
	s_add_u32 s0, s90, s8
	v_lshl_add_u64 v[10:11], s[90:91], 0, v[4:5]
	s_addc_u32 s1, s91, s9
	v_add_co_u32_e32 v30, vcc, s5, v10
	s_add_u32 s14, s0, 0x5900000
	s_nop 0
	v_addc_co_u32_e32 v31, vcc, 0, v11, vcc
	global_load_dwordx4 v[10:13], v0, s[0:1]
	s_addc_u32 s15, s1, 0
	global_load_dwordx4 v[14:17], v1, s[14:15] offset:48
	global_load_dwordx4 v[18:21], v1, s[14:15] offset:32
	global_load_dwordx4 v[22:25], v1, s[14:15] offset:16
	global_load_dwordx2 v[32:33], v[30:31], off
	global_load_dwordx4 v[26:29], v[2:3], off
	s_add_i32 s2, s2, s4
	s_add_u32 s8, s8, s10
	s_addc_u32 s9, s9, s11
	v_lshl_add_u64 v[4:5], v[4:5], 0, s[6:7]
	s_cmp_lt_i32 s2, s16
	s_waitcnt vmcnt(3)
	v_add_f32_e32 v18, v18, v19
	v_mov_b32_e32 v34, v11
	v_mov_b32_e32 v35, v12
	v_mov_b32_e32 v11, v13
	v_pk_add_f32 v[10:11], v[34:35], v[10:11]
	s_waitcnt vmcnt(2)
	v_mov_b32_e32 v34, v23
	v_mov_b32_e32 v35, v24
	v_mov_b32_e32 v23, v25
	v_add_f32_e32 v20, v20, v21
	v_mov_b32_e32 v19, v16
	v_mov_b32_e32 v21, v17
	v_pk_add_f32 v[16:17], v[34:35], v[22:23]
	v_pk_add_f32 v[10:11], v[10:11], v[10:11] op_sel:[0,1] op_sel_hi:[1,0]
	v_pk_add_f32 v[16:17], v[16:17], v[16:17] op_sel:[0,1] op_sel_hi:[1,0]
	v_mov_b32_e32 v11, v14
	v_mov_b32_e32 v17, v15
	v_pk_add_f32 v[18:19], v[18:19], v[20:21]
	v_pk_add_f32 v[10:11], v[10:11], v[16:17]
	s_waitcnt vmcnt(1)
	v_lshlrev_b32_e32 v12, 16, v32
	v_pk_add_f32 v[10:11], v[10:11], v[18:19]
	v_and_b32_e32 v13, 0xffff0000, v32
	v_add_f32_e32 v10, v10, v11
	v_fmamk_f32 v10, v10, 0x3a800000, v8
	v_mul_f32_e32 v11, 0x4f800000, v10
	v_cmp_gt_f32_e32 vcc, s3, v10
	v_lshlrev_b32_e32 v32, 16, v33
	v_and_b32_e32 v33, 0xffff0000, v33
	v_cndmask_b32_e32 v10, v10, v11, vcc
	v_sqrt_f32_e32 v11, v10
	s_nop 0
	v_add_u32_e32 v14, -1, v11
	v_add_u32_e32 v15, 1, v11
	v_fma_f32 v16, -v14, v11, v10
	v_fma_f32 v17, -v15, v11, v10
	v_cmp_ge_f32_e64 s[0:1], 0, v16
	s_nop 1
	v_cndmask_b32_e64 v11, v11, v14, s[0:1]
	v_cmp_lt_f32_e64 s[0:1], 0, v17
	s_nop 1
	v_cndmask_b32_e64 v11, v11, v15, s[0:1]
	v_mul_f32_e32 v14, 0x37800000, v11
	v_cndmask_b32_e32 v11, v11, v14, vcc
	v_cmp_class_f32_e32 vcc, v10, v9
	s_nop 1
	v_cndmask_b32_e32 v10, v11, v10, vcc
	v_div_scale_f32 v11, s[0:1], v10, v10, 1.0
	v_rcp_f32_e32 v15, v11
	v_div_scale_f32 v14, vcc, 1.0, v10, 1.0
	v_fma_f32 v16, -v11, v15, 1.0
	v_fmac_f32_e32 v15, v16, v15
	v_mul_f32_e32 v16, v14, v15
	v_fma_f32 v17, -v11, v16, v14
	v_fmac_f32_e32 v16, v17, v15
	v_fma_f32 v11, -v11, v16, v14
	v_div_fmas_f32 v11, v11, v15, v16
	v_div_fixup_f32 v14, v11, v10, 1.0
	v_pk_mul_f32 v[10:11], v[14:15], v[12:13] op_sel_hi:[0,1]
	v_pk_mul_f32 v[12:13], v[14:15], v[32:33] op_sel_hi:[0,1]
	s_waitcnt vmcnt(0)
	v_pk_mul_f32 v[12:13], v[28:29], v[12:13]
	v_pk_mul_f32 v[10:11], v[26:27], v[10:11]
	global_store_dwordx4 v[6:7], v[10:13], off offset:-3072 nt
	global_load_dwordx2 v[16:17], v[30:31], off offset:512
	s_nop 0
	global_load_dwordx4 v[10:13], v[2:3], off offset:1024
	s_waitcnt vmcnt(1)
	v_lshlrev_b32_e32 v18, 16, v16
	v_and_b32_e32 v19, 0xffff0000, v16
	v_lshlrev_b32_e32 v16, 16, v17
	v_and_b32_e32 v17, 0xffff0000, v17
	v_pk_mul_f32 v[18:19], v[14:15], v[18:19] op_sel_hi:[0,1]
	v_pk_mul_f32 v[16:17], v[14:15], v[16:17] op_sel_hi:[0,1]
	s_waitcnt vmcnt(0)
	v_pk_mul_f32 v[12:13], v[12:13], v[16:17]
	v_pk_mul_f32 v[10:11], v[10:11], v[18:19]
	global_store_dwordx4 v[6:7], v[10:13], off offset:-2048 nt
	global_load_dwordx2 v[16:17], v[30:31], off offset:1024
	s_nop 0
	global_load_dwordx4 v[10:13], v[2:3], off offset:2048
	s_waitcnt vmcnt(1)
	v_lshlrev_b32_e32 v18, 16, v16
	v_and_b32_e32 v19, 0xffff0000, v16
	v_lshlrev_b32_e32 v16, 16, v17
	v_and_b32_e32 v17, 0xffff0000, v17
	v_pk_mul_f32 v[18:19], v[14:15], v[18:19] op_sel_hi:[0,1]
	v_pk_mul_f32 v[16:17], v[14:15], v[16:17] op_sel_hi:[0,1]
	s_waitcnt vmcnt(0)
	v_pk_mul_f32 v[12:13], v[12:13], v[16:17]
	v_pk_mul_f32 v[10:11], v[10:11], v[18:19]
	global_store_dwordx4 v[6:7], v[10:13], off offset:-1024 nt
	global_load_dwordx2 v[16:17], v[30:31], off offset:1536
	s_nop 0
	global_load_dwordx4 v[10:13], v[2:3], off offset:3072
	s_waitcnt vmcnt(1)
	v_lshlrev_b32_e32 v18, 16, v16
	v_and_b32_e32 v19, 0xffff0000, v16
	v_lshlrev_b32_e32 v16, 16, v17
	v_and_b32_e32 v17, 0xffff0000, v17
	v_pk_mul_f32 v[18:19], v[14:15], v[18:19] op_sel_hi:[0,1]
	v_pk_mul_f32 v[14:15], v[14:15], v[16:17] op_sel_hi:[0,1]
	s_waitcnt vmcnt(0)
	v_pk_mul_f32 v[12:13], v[12:13], v[14:15]
	v_pk_mul_f32 v[10:11], v[10:11], v[18:19]
	global_store_dwordx4 v[6:7], v[10:13], off nt
	v_lshl_add_u64 v[6:7], v[6:7], 0, s[12:13]
	s_cbranch_scc1 .LBB0_2089
